# DSA attention: coalesced key-row gathers (8 lanes per 128-B row) transposed into MFMA operand layout through a per-wave LDS staging tile
# speedup vs baseline: 1.0065x; 1.0065x over previous
;   __device__ __forceinline__ half_t* mm() const { return (half_t*)(ws() + OFF_mm); }
; __device__ __forceinline__ void dsa_item(const KP& p, int b, int tile, char* smem) {
;     ...
;     const int nsel = min(cnt[tk], 256);
;     const half_t* urow = ub + (size_t)t * NU;
;     const int col = lane & 15;
;     h8 q0, q1;
; #pragma unroll
;     for (int e = 0; e < 8; ++e) { q0[e] = (half_t)0.f; q1[e] = (half_t)0.f; }
;     if (col < 8) {
;       q0 = *(const h8*)(urow + C_BQ + col * 64 + hq * 8);
;       q1 = *(const h8*)(urow + C_BQ + col * 64 + 32 + hq * 8);
;     }
;     float mx = NEGF;
; #pragma unroll 1
;     for (int mg = 0; mg < 2; ++mg) {
; #pragma unroll
;       for (int mm = 0; mm < 8; ++mm) {
;         const int m = mg * 8 + mm;
;         const int pos = m * 16 + col;
;         const int s = (pos < nsel) ? (int)sel[tk * 256 + pos] : 0;
;         const half_t* kp = ub + (size_t)s * NU + C_BK + hq * 8;
;         const h8 a0 = *(const h8*)kp, a1 = *(const h8*)(kp + 32);
.LBB0_1427:
	s_or_b64 exec, exec, s[2:3]
	s_waitcnt lgkmcnt(0)
	v_min_i32_e32 v85, 0x100, v11
	v_lshlrev_b32_e32 v14, 9, v10
	v_mov_b32_e32 v15, 0xf149f2ca
	s_add_u32 s14, s78, 0x3800
	s_addc_u32 s15, s79, 0
	v_and_b32_e32 v200, 7, v157
	v_lshlrev_b32_e32 v200, 4, v200
	v_mul_u32_u24_e32 v201, 0x240, v159
	v_add_u32_e32 v201, 0xa800, v201
	v_mul_u32_u24_e32 v198, 0x90, v165
	v_add3_u32 v198, v198, v200, v201
	v_mul_u32_u24_e32 v199, 0x90, v157
	v_add3_u32 v199, v199, v126, v201
	v_lshl_add_u32 v80, v165, 1, v14
	v_add_u32_e32 v171, -1, v85
	v_add_u32_e32 v156, -2, v85
	v_add_u32_e32 v158, -3, v85
	ds_read_u16 v172, v80 offset:32768
	ds_read_u16 v173, v80 offset:32800
	ds_read_u16 v174, v80 offset:32832
	ds_read_u16 v175, v80 offset:32864
	ds_read_u16 v176, v80 offset:32896
	ds_read_u16 v177, v80 offset:32928
	ds_read_u16 v178, v80 offset:32960
	ds_read_u16 v179, v80 offset:32992
	ds_read_u16 v180, v80 offset:33024
	ds_read_u16 v181, v80 offset:33056
	ds_read_u16 v188, v80 offset:33088
	ds_read_u16 v189, v80 offset:33120
	ds_read_u16 v190, v80 offset:33152
	ds_read_u16 v191, v80 offset:33184
	ds_read_u16 v192, v80 offset:33216
	ds_read_u16 v193, v80 offset:33248
	v_or_b32_e32 v81, 0, v165
	v_cmp_lt_i32_e32 vcc, v81, v85
	s_waitcnt lgkmcnt(15)
	s_nop 0
	v_cndmask_b32_e32 v172, 0, v172, vcc
	v_mul_u32_u24_e32 v172, 0x1d00, v172
	v_lshl_add_u32 v172, v172, 1, v200
	global_load_dwordx4 v[16:19], v172, s[14:15]
	v_or_b32_e32 v81, 16, v165
	v_cmp_lt_i32_e32 vcc, v81, v85
	s_waitcnt lgkmcnt(14)
	s_nop 0
	v_cndmask_b32_e32 v173, 0, v173, vcc
	v_mul_u32_u24_e32 v173, 0x1d00, v173
	v_lshl_add_u32 v173, v173, 1, v200
	global_load_dwordx4 v[24:27], v173, s[14:15]
	v_or_b32_e32 v81, 32, v165
	v_cmp_lt_i32_e32 vcc, v81, v85
	s_waitcnt lgkmcnt(13)
	s_nop 0
	v_cndmask_b32_e32 v174, 0, v174, vcc
	v_mul_u32_u24_e32 v174, 0x1d00, v174
	v_lshl_add_u32 v174, v174, 1, v200
	global_load_dwordx4 v[32:35], v174, s[14:15]
	v_or_b32_e32 v81, 48, v165
	v_cmp_lt_i32_e32 vcc, v81, v85
	s_waitcnt lgkmcnt(12)
	s_nop 0
	v_cndmask_b32_e32 v175, 0, v175, vcc
	v_mul_u32_u24_e32 v175, 0x1d00, v175
	v_lshl_add_u32 v175, v175, 1, v200
	global_load_dwordx4 v[40:43], v175, s[14:15]
	v_or_b32_e32 v81, 64, v165
	v_cmp_lt_i32_e32 vcc, v81, v85
	s_waitcnt lgkmcnt(11)
	s_nop 0
	v_cndmask_b32_e32 v176, 0, v176, vcc
	v_mul_u32_u24_e32 v176, 0x1d00, v176
	v_lshl_add_u32 v176, v176, 1, v200
	global_load_dwordx4 v[48:51], v176, s[14:15]
	v_or_b32_e32 v81, 0x50, v165
	v_cmp_lt_i32_e32 vcc, v81, v85
	s_waitcnt lgkmcnt(10)
	s_nop 0
	v_cndmask_b32_e32 v177, 0, v177, vcc
	v_mul_u32_u24_e32 v177, 0x1d00, v177
	v_lshl_add_u32 v177, v177, 1, v200
	global_load_dwordx4 v[56:59], v177, s[14:15]
	v_or_b32_e32 v81, 0x60, v165
	v_cmp_lt_i32_e32 vcc, v81, v85
	s_waitcnt lgkmcnt(9)
	s_nop 0
	v_cndmask_b32_e32 v178, 0, v178, vcc
	v_mul_u32_u24_e32 v178, 0x1d00, v178
	v_lshl_add_u32 v178, v178, 1, v200
	global_load_dwordx4 v[64:67], v178, s[14:15]
	v_or_b32_e32 v81, 0x70, v165
	v_cmp_lt_i32_e32 vcc, v81, v85
	s_waitcnt lgkmcnt(8)
	s_nop 0
	v_cndmask_b32_e32 v179, 0, v179, vcc
	v_mul_u32_u24_e32 v179, 0x1d00, v179
	v_lshl_add_u32 v179, v179, 1, v200
	global_load_dwordx4 v[72:75], v179, s[14:15]
	v_or_b32_e32 v81, 0x80, v165
	v_cmp_lt_i32_e32 vcc, v81, v85
	s_waitcnt lgkmcnt(7)
	s_nop 0
	v_cndmask_b32_e32 v180, 0, v180, vcc
	v_mul_u32_u24_e32 v180, 0x1d00, v180
	v_lshl_add_u32 v180, v180, 1, v200
	global_load_dwordx4 v[90:93], v180, s[14:15]
	v_or_b32_e32 v81, 0x90, v165
	v_cmp_lt_i32_e32 vcc, v81, v85
	s_waitcnt lgkmcnt(6)
	s_nop 0
	v_cndmask_b32_e32 v181, 0, v181, vcc
	v_mul_u32_u24_e32 v181, 0x1d00, v181
	v_lshl_add_u32 v181, v181, 1, v200
	global_load_dwordx4 v[98:101], v181, s[14:15]
	v_or_b32_e32 v81, 0xa0, v165
	v_cmp_lt_i32_e32 vcc, v81, v85
	s_waitcnt lgkmcnt(5)
	s_nop 0
	v_cndmask_b32_e32 v188, 0, v188, vcc
	v_mul_u32_u24_e32 v188, 0x1d00, v188
	v_lshl_add_u32 v188, v188, 1, v200
	global_load_dwordx4 v[106:109], v188, s[14:15]
	v_or_b32_e32 v81, 0xb0, v165
	v_cmp_lt_i32_e32 vcc, v81, v85
	s_waitcnt lgkmcnt(4)
	s_nop 0
	v_cndmask_b32_e32 v189, 0, v189, vcc
	v_mul_u32_u24_e32 v189, 0x1d00, v189
	v_lshl_add_u32 v189, v189, 1, v200
	global_load_dwordx4 v[114:117], v189, s[14:15]
	v_or_b32_e32 v81, 0xc0, v165
	v_cmp_lt_i32_e32 vcc, v81, v85
	s_waitcnt lgkmcnt(3)
	s_nop 0
	v_cndmask_b32_e32 v190, 0, v190, vcc
	v_mul_u32_u24_e32 v190, 0x1d00, v190
	v_lshl_add_u32 v190, v190, 1, v200
	global_load_dwordx4 v[122:125], v190, s[14:15]
	v_or_b32_e32 v81, 0xd0, v165
	v_cmp_lt_i32_e32 vcc, v81, v85
	s_waitcnt lgkmcnt(2)
	s_nop 0
	v_cndmask_b32_e32 v191, 0, v191, vcc
	v_mul_u32_u24_e32 v191, 0x1d00, v191
	v_lshl_add_u32 v191, v191, 1, v200
	global_load_dwordx4 v[132:135], v191, s[14:15]
	v_or_b32_e32 v81, 0xe0, v165
	v_cmp_lt_i32_e32 vcc, v81, v85
	s_waitcnt lgkmcnt(1)
	s_nop 0
	v_cndmask_b32_e32 v192, 0, v192, vcc
	v_mul_u32_u24_e32 v192, 0x1d00, v192
	v_lshl_add_u32 v192, v192, 1, v200
	global_load_dwordx4 v[140:143], v192, s[14:15]
	v_or_b32_e32 v81, 0xf0, v165
	v_cmp_lt_i32_e32 vcc, v81, v85
	s_waitcnt lgkmcnt(0)
	s_nop 0
	v_cndmask_b32_e32 v193, 0, v193, vcc
	v_mul_u32_u24_e32 v193, 0x1d00, v193
	v_lshl_add_u32 v193, v193, 1, v200
	global_load_dwordx4 v[148:151], v193, s[14:15]
	ds_read_u16 v172, v80 offset:32784
	ds_read_u16 v173, v80 offset:32816
	ds_read_u16 v174, v80 offset:32848
	ds_read_u16 v175, v80 offset:32880
	ds_read_u16 v176, v80 offset:32912
	ds_read_u16 v177, v80 offset:32944
	ds_read_u16 v178, v80 offset:32976
	ds_read_u16 v179, v80 offset:33008
	ds_read_u16 v180, v80 offset:33040
	ds_read_u16 v181, v80 offset:33072
	ds_read_u16 v188, v80 offset:33104
	ds_read_u16 v189, v80 offset:33136
	ds_read_u16 v190, v80 offset:33168
	ds_read_u16 v191, v80 offset:33200
	ds_read_u16 v192, v80 offset:33232
	ds_read_u16 v193, v80 offset:33264
	v_or_b32_e32 v81, 8, v165
	v_cmp_lt_i32_e32 vcc, v81, v85
	s_waitcnt lgkmcnt(15)
;   __device__ __forceinline__ half_t* mm() const { return (half_t*)(ws() + OFF_mm); }
; __device__ __forceinline__ void dsa_item(const KP& p, int b, int tile, char* smem) {
;     ...
; #pragma unroll
;       for (int mm = 0; mm < 8; ++mm) {
;         const int m = mg * 8 + mm;
;         const int pos = m * 16 + col;
;         const int s = (pos < nsel) ? (int)sel[tk * 256 + pos] : 0;
;         const half_t* kp = ub + (size_t)s * NU + C_BK + hq * 8;
;         const h8 a0 = *(const h8*)kp, a1 = *(const h8*)(kp + 32);
;         f32x4 d = {0.f, 0.f, 0.f, 0.f};
;         d = __builtin_amdgcn_mfma_f32_16x16x32_f16(a0, q0, d, 0, 0, 0);
;         d = __builtin_amdgcn_mfma_f32_16x16x32_f16(a1, q1, d, 0, 0, 0);
; #pragma unroll
;         for (int r = 0; r < 4; ++r) {
;           const int pp = m * 16 + hq * 4 + r;
;           const float v = (pp < nsel) ? d[r] * 0.125f : NEGF;
;           mx = fmaxf(mx, v);
;           if (col < 8) pbuf[pp * 8 + col] = v;
;         }
;       }
	s_nop 0
	v_cndmask_b32_e32 v172, 0, v172, vcc
	v_mul_u32_u24_e32 v172, 0x1d00, v172
	v_lshl_add_u32 v172, v172, 1, v200
	global_load_dwordx4 v[20:23], v172, s[14:15]
	v_or_b32_e32 v81, 24, v165
	v_cmp_lt_i32_e32 vcc, v81, v85
	s_waitcnt lgkmcnt(14)
	s_nop 0
	v_cndmask_b32_e32 v173, 0, v173, vcc
	v_mul_u32_u24_e32 v173, 0x1d00, v173
	v_lshl_add_u32 v173, v173, 1, v200
	global_load_dwordx4 v[28:31], v173, s[14:15]
	v_or_b32_e32 v81, 40, v165
	v_cmp_lt_i32_e32 vcc, v81, v85
	s_waitcnt lgkmcnt(13)
	s_nop 0
	v_cndmask_b32_e32 v174, 0, v174, vcc
	v_mul_u32_u24_e32 v174, 0x1d00, v174
	v_lshl_add_u32 v174, v174, 1, v200
	global_load_dwordx4 v[36:39], v174, s[14:15]
	v_or_b32_e32 v81, 56, v165
	v_cmp_lt_i32_e32 vcc, v81, v85
	s_waitcnt lgkmcnt(12)
	s_nop 0
	v_cndmask_b32_e32 v175, 0, v175, vcc
	v_mul_u32_u24_e32 v175, 0x1d00, v175
	v_lshl_add_u32 v175, v175, 1, v200
	global_load_dwordx4 v[44:47], v175, s[14:15]
	v_or_b32_e32 v81, 0x48, v165
	v_cmp_lt_i32_e32 vcc, v81, v85
	s_waitcnt lgkmcnt(11)
	s_nop 0
	v_cndmask_b32_e32 v176, 0, v176, vcc
	v_mul_u32_u24_e32 v176, 0x1d00, v176
	v_lshl_add_u32 v176, v176, 1, v200
	global_load_dwordx4 v[52:55], v176, s[14:15]
	v_or_b32_e32 v81, 0x58, v165
	v_cmp_lt_i32_e32 vcc, v81, v85
	s_waitcnt lgkmcnt(10)
	s_nop 0
	v_cndmask_b32_e32 v177, 0, v177, vcc
	v_mul_u32_u24_e32 v177, 0x1d00, v177
	v_lshl_add_u32 v177, v177, 1, v200
	global_load_dwordx4 v[60:63], v177, s[14:15]
	v_or_b32_e32 v81, 0x68, v165
	v_cmp_lt_i32_e32 vcc, v81, v85
	s_waitcnt lgkmcnt(9)
	s_nop 0
	v_cndmask_b32_e32 v178, 0, v178, vcc
	v_mul_u32_u24_e32 v178, 0x1d00, v178
	v_lshl_add_u32 v178, v178, 1, v200
	global_load_dwordx4 v[68:71], v178, s[14:15]
	v_or_b32_e32 v81, 0x78, v165
	v_cmp_lt_i32_e32 vcc, v81, v85
	s_waitcnt lgkmcnt(8)
	s_nop 0
	v_cndmask_b32_e32 v179, 0, v179, vcc
	v_mul_u32_u24_e32 v179, 0x1d00, v179
	v_lshl_add_u32 v179, v179, 1, v200
	global_load_dwordx4 v[76:79], v179, s[14:15]
	v_or_b32_e32 v81, 0x88, v165
	v_cmp_lt_i32_e32 vcc, v81, v85
	s_waitcnt lgkmcnt(7)
	s_nop 0
	v_cndmask_b32_e32 v180, 0, v180, vcc
	v_mul_u32_u24_e32 v180, 0x1d00, v180
	v_lshl_add_u32 v180, v180, 1, v200
	global_load_dwordx4 v[94:97], v180, s[14:15]
	v_or_b32_e32 v81, 0x98, v165
	v_cmp_lt_i32_e32 vcc, v81, v85
	s_waitcnt lgkmcnt(6)
	s_nop 0
	v_cndmask_b32_e32 v181, 0, v181, vcc
	v_mul_u32_u24_e32 v181, 0x1d00, v181
	v_lshl_add_u32 v181, v181, 1, v200
	global_load_dwordx4 v[102:105], v181, s[14:15]
	v_or_b32_e32 v81, 0xa8, v165
	v_cmp_lt_i32_e32 vcc, v81, v85
	s_waitcnt lgkmcnt(5)
	s_nop 0
	v_cndmask_b32_e32 v188, 0, v188, vcc
	v_mul_u32_u24_e32 v188, 0x1d00, v188
	v_lshl_add_u32 v188, v188, 1, v200
	global_load_dwordx4 v[110:113], v188, s[14:15]
	v_or_b32_e32 v81, 0xb8, v165
	v_cmp_lt_i32_e32 vcc, v81, v85
	s_waitcnt lgkmcnt(4)
	s_nop 0
	v_cndmask_b32_e32 v189, 0, v189, vcc
	v_mul_u32_u24_e32 v189, 0x1d00, v189
	v_lshl_add_u32 v189, v189, 1, v200
	global_load_dwordx4 v[118:121], v189, s[14:15]
	v_or_b32_e32 v81, 0xc8, v165
	v_cmp_lt_i32_e32 vcc, v81, v85
	s_waitcnt lgkmcnt(3)
	s_nop 0
	v_cndmask_b32_e32 v190, 0, v190, vcc
	v_mul_u32_u24_e32 v190, 0x1d00, v190
	v_lshl_add_u32 v190, v190, 1, v200
	global_load_dwordx4 v[128:131], v190, s[14:15]
	v_or_b32_e32 v81, 0xd8, v165
	v_cmp_lt_i32_e32 vcc, v81, v85
	s_waitcnt lgkmcnt(2)
	s_nop 0
	v_cndmask_b32_e32 v191, 0, v191, vcc
	v_mul_u32_u24_e32 v191, 0x1d00, v191
	v_lshl_add_u32 v191, v191, 1, v200
	global_load_dwordx4 v[136:139], v191, s[14:15]
	v_or_b32_e32 v81, 0xe8, v165
	v_cmp_lt_i32_e32 vcc, v81, v85
	s_waitcnt lgkmcnt(1)
	s_nop 0
	v_cndmask_b32_e32 v192, 0, v192, vcc
	v_mul_u32_u24_e32 v192, 0x1d00, v192
	v_lshl_add_u32 v192, v192, 1, v200
	global_load_dwordx4 v[144:147], v192, s[14:15]
	v_or_b32_e32 v81, 0xf8, v165
	v_cmp_lt_i32_e32 vcc, v81, v85
	s_waitcnt lgkmcnt(0)
	s_nop 0
	v_cndmask_b32_e32 v193, 0, v193, vcc
	v_mul_u32_u24_e32 v193, 0x1d00, v193
	v_lshl_add_u32 v193, v193, 1, v200
	global_load_dwordx4 v[152:155], v193, s[14:15]
	s_waitcnt vmcnt(15)
	ds_write_b128 v198, v[16:19]
	ds_write_b128 v198, v[20:23] offset:1152
	ds_read_b128 v[16:19], v199
	ds_read_b128 v[20:23], v199 offset:64
	s_waitcnt vmcnt(14)
	ds_write_b128 v198, v[24:27]
	ds_write_b128 v198, v[28:31] offset:1152
	ds_read_b128 v[24:27], v199
	ds_read_b128 v[28:31], v199 offset:64
	s_waitcnt lgkmcnt(4)
	v_mfma_f32_16x16x32_f16 v[10:13], v[16:19], v[6:9], 0
	v_mfma_f32_16x16x32_f16 v[10:13], v[20:23], v[2:5], v[10:13]
	s_nop 4
	s_waitcnt vmcnt(13)
	ds_write_b128 v198, v[32:35]
	ds_write_b128 v198, v[36:39] offset:1152
	ds_read_b128 v[32:35], v199
	ds_read_b128 v[36:39], v199 offset:64
	s_waitcnt lgkmcnt(4)
	v_mfma_f32_16x16x32_f16 v[194:197], v[24:27], v[6:9], 0
	v_mfma_f32_16x16x32_f16 v[194:197], v[28:31], v[2:5], v[194:197]
	v_or_b32_e32 v80, 0, v160
	v_mul_f32_e32 v10, 0x3e000000, v10
	v_mul_f32_e32 v11, 0x3e000000, v11
	v_mul_f32_e32 v12, 0x3e000000, v12
	v_mul_f32_e32 v13, 0x3e000000, v13
	v_cmp_lt_i32_e32 vcc, v80, v85
	v_cmp_lt_i32_e64 s[46:47], v80, v171
	v_lshl_add_u32 v81, v80, 5, v167
	s_nop 0
	v_cndmask_b32_e32 v10, v242, v10, vcc
	v_cndmask_b32_e64 v11, v242, v11, s[46:47]
	v_cmp_lt_i32_e32 vcc, v80, v156
	v_cmp_lt_i32_e64 s[46:47], v80, v158
	v_max3_f32 v15, v15, v10, v11
	s_nop 0
	v_cndmask_b32_e32 v12, v242, v12, vcc
	v_cndmask_b32_e64 v13, v242, v13, s[46:47]
	v_max3_f32 v15, v15, v12, v13
	s_and_saveexec_b64 s[2:3], s[38:39]
	ds_write_b32 v81, v10
	ds_write_b32 v81, v11 offset:32
	ds_write_b32 v81, v12 offset:64
	ds_write_b32 v81, v13 offset:96
	s_or_b64 exec, exec, s[2:3]
	s_waitcnt vmcnt(12)
	ds_write_b128 v198, v[40:43]
	ds_write_b128 v198, v[44:47] offset:1152
	ds_read_b128 v[40:43], v199
	ds_read_b128 v[44:47], v199 offset:64
	s_waitcnt lgkmcnt(8)
;   __device__ __forceinline__ half_t* mm() const { return (half_t*)(ws() + OFF_mm); }
; __device__ __forceinline__ void dsa_item(const KP& p, int b, int tile, char* smem) {
;     ...
; #pragma unroll
;       for (int mm = 0; mm < 8; ++mm) {
;         const int m = mg * 8 + mm;
;         const int pos = m * 16 + col;
;         const int s = (pos < nsel) ? (int)sel[tk * 256 + pos] : 0;
;         const half_t* kp = ub + (size_t)s * NU + C_BK + hq * 8;
;         const h8 a0 = *(const h8*)kp, a1 = *(const h8*)(kp + 32);
;         f32x4 d = {0.f, 0.f, 0.f, 0.f};
;         d = __builtin_amdgcn_mfma_f32_16x16x32_f16(a0, q0, d, 0, 0, 0);
;         d = __builtin_amdgcn_mfma_f32_16x16x32_f16(a1, q1, d, 0, 0, 0);
; #pragma unroll
;         for (int r = 0; r < 4; ++r) {
;           const int pp = m * 16 + hq * 4 + r;
;           const float v = (pp < nsel) ? d[r] * 0.125f : NEGF;
;           mx = fmaxf(mx, v);
;           if (col < 8) pbuf[pp * 8 + col] = v;
;         }
;       }
	v_mfma_f32_16x16x32_f16 v[10:13], v[32:35], v[6:9], 0
	v_mfma_f32_16x16x32_f16 v[10:13], v[36:39], v[2:5], v[10:13]
	v_or_b32_e32 v80, 16, v160
	v_mul_f32_e32 v194, 0x3e000000, v194
	v_mul_f32_e32 v195, 0x3e000000, v195
	v_mul_f32_e32 v196, 0x3e000000, v196
	v_mul_f32_e32 v197, 0x3e000000, v197
	v_cmp_lt_i32_e32 vcc, v80, v85
	v_cmp_lt_i32_e64 s[46:47], v80, v171
	v_lshl_add_u32 v81, v80, 5, v167
	s_nop 0
	v_cndmask_b32_e32 v194, v242, v194, vcc
	v_cndmask_b32_e64 v195, v242, v195, s[46:47]
	v_cmp_lt_i32_e32 vcc, v80, v156
	v_cmp_lt_i32_e64 s[46:47], v80, v158
	v_max3_f32 v15, v15, v194, v195
	s_nop 0
	v_cndmask_b32_e32 v196, v242, v196, vcc
	v_cndmask_b32_e64 v197, v242, v197, s[46:47]
	v_max3_f32 v15, v15, v196, v197
	s_and_saveexec_b64 s[2:3], s[38:39]
	ds_write_b32 v81, v194
	ds_write_b32 v81, v195 offset:32
	ds_write_b32 v81, v196 offset:64
	ds_write_b32 v81, v197 offset:96
	s_or_b64 exec, exec, s[2:3]
	s_waitcnt vmcnt(11)
	ds_write_b128 v198, v[48:51]
	ds_write_b128 v198, v[52:55] offset:1152
	ds_read_b128 v[48:51], v199
	ds_read_b128 v[52:55], v199 offset:64
	s_waitcnt lgkmcnt(8)
	v_mfma_f32_16x16x32_f16 v[194:197], v[40:43], v[6:9], 0
	v_mfma_f32_16x16x32_f16 v[194:197], v[44:47], v[2:5], v[194:197]
	v_or_b32_e32 v80, 32, v160
	v_mul_f32_e32 v10, 0x3e000000, v10
	v_mul_f32_e32 v11, 0x3e000000, v11
	v_mul_f32_e32 v12, 0x3e000000, v12
	v_mul_f32_e32 v13, 0x3e000000, v13
	v_cmp_lt_i32_e32 vcc, v80, v85
	v_cmp_lt_i32_e64 s[46:47], v80, v171
	v_lshl_add_u32 v81, v80, 5, v167
	s_nop 0
	v_cndmask_b32_e32 v10, v242, v10, vcc
	v_cndmask_b32_e64 v11, v242, v11, s[46:47]
	v_cmp_lt_i32_e32 vcc, v80, v156
	v_cmp_lt_i32_e64 s[46:47], v80, v158
	v_max3_f32 v15, v15, v10, v11
	s_nop 0
	v_cndmask_b32_e32 v12, v242, v12, vcc
	v_cndmask_b32_e64 v13, v242, v13, s[46:47]
	v_max3_f32 v15, v15, v12, v13
	s_and_saveexec_b64 s[2:3], s[38:39]
	ds_write_b32 v81, v10
	ds_write_b32 v81, v11 offset:32
	ds_write_b32 v81, v12 offset:64
	ds_write_b32 v81, v13 offset:96
	s_or_b64 exec, exec, s[2:3]
	s_waitcnt vmcnt(10)
	ds_write_b128 v198, v[56:59]
	ds_write_b128 v198, v[60:63] offset:1152
	ds_read_b128 v[56:59], v199
	ds_read_b128 v[60:63], v199 offset:64
	s_waitcnt lgkmcnt(8)
	v_mfma_f32_16x16x32_f16 v[10:13], v[48:51], v[6:9], 0
	v_mfma_f32_16x16x32_f16 v[10:13], v[52:55], v[2:5], v[10:13]
	v_or_b32_e32 v80, 48, v160
	v_mul_f32_e32 v194, 0x3e000000, v194
	v_mul_f32_e32 v195, 0x3e000000, v195
	v_mul_f32_e32 v196, 0x3e000000, v196
	v_mul_f32_e32 v197, 0x3e000000, v197
	v_cmp_lt_i32_e32 vcc, v80, v85
	v_cmp_lt_i32_e64 s[46:47], v80, v171
	v_lshl_add_u32 v81, v80, 5, v167
	s_nop 0
	v_cndmask_b32_e32 v194, v242, v194, vcc
	v_cndmask_b32_e64 v195, v242, v195, s[46:47]
	v_cmp_lt_i32_e32 vcc, v80, v156
	v_cmp_lt_i32_e64 s[46:47], v80, v158
	v_max3_f32 v15, v15, v194, v195
	s_nop 0
	v_cndmask_b32_e32 v196, v242, v196, vcc
	v_cndmask_b32_e64 v197, v242, v197, s[46:47]
	v_max3_f32 v15, v15, v196, v197
	s_and_saveexec_b64 s[2:3], s[38:39]
	ds_write_b32 v81, v194
	ds_write_b32 v81, v195 offset:32
	ds_write_b32 v81, v196 offset:64
	ds_write_b32 v81, v197 offset:96
	s_or_b64 exec, exec, s[2:3]
	s_waitcnt vmcnt(9)
	ds_write_b128 v198, v[64:67]
	ds_write_b128 v198, v[68:71] offset:1152
	ds_read_b128 v[64:67], v199
	ds_read_b128 v[68:71], v199 offset:64
	s_waitcnt lgkmcnt(8)
	v_mfma_f32_16x16x32_f16 v[194:197], v[56:59], v[6:9], 0
	v_mfma_f32_16x16x32_f16 v[194:197], v[60:63], v[2:5], v[194:197]
	v_or_b32_e32 v80, 64, v160
	v_mul_f32_e32 v10, 0x3e000000, v10
	v_mul_f32_e32 v11, 0x3e000000, v11
	v_mul_f32_e32 v12, 0x3e000000, v12
	v_mul_f32_e32 v13, 0x3e000000, v13
	v_cmp_lt_i32_e32 vcc, v80, v85
	v_cmp_lt_i32_e64 s[46:47], v80, v171
	v_lshl_add_u32 v81, v80, 5, v167
	s_nop 0
	v_cndmask_b32_e32 v10, v242, v10, vcc
	v_cndmask_b32_e64 v11, v242, v11, s[46:47]
	v_cmp_lt_i32_e32 vcc, v80, v156
	v_cmp_lt_i32_e64 s[46:47], v80, v158
	v_max3_f32 v15, v15, v10, v11
	s_nop 0
	v_cndmask_b32_e32 v12, v242, v12, vcc
	v_cndmask_b32_e64 v13, v242, v13, s[46:47]
	v_max3_f32 v15, v15, v12, v13
	s_and_saveexec_b64 s[2:3], s[38:39]
	ds_write_b32 v81, v10
	ds_write_b32 v81, v11 offset:32
	ds_write_b32 v81, v12 offset:64
	ds_write_b32 v81, v13 offset:96
	s_or_b64 exec, exec, s[2:3]
	s_waitcnt vmcnt(8)
	ds_write_b128 v198, v[72:75]
	ds_write_b128 v198, v[76:79] offset:1152
	ds_read_b128 v[72:75], v199
	ds_read_b128 v[76:79], v199 offset:64
	s_waitcnt lgkmcnt(8)
	v_mfma_f32_16x16x32_f16 v[10:13], v[64:67], v[6:9], 0
	v_mfma_f32_16x16x32_f16 v[10:13], v[68:71], v[2:5], v[10:13]
	v_or_b32_e32 v80, 0x50, v160
	v_mul_f32_e32 v194, 0x3e000000, v194
	v_mul_f32_e32 v195, 0x3e000000, v195
	v_mul_f32_e32 v196, 0x3e000000, v196
	v_mul_f32_e32 v197, 0x3e000000, v197
	v_cmp_lt_i32_e32 vcc, v80, v85
	v_cmp_lt_i32_e64 s[46:47], v80, v171
	v_lshl_add_u32 v81, v80, 5, v167
	s_nop 0
	v_cndmask_b32_e32 v194, v242, v194, vcc
	v_cndmask_b32_e64 v195, v242, v195, s[46:47]
	v_cmp_lt_i32_e32 vcc, v80, v156
	v_cmp_lt_i32_e64 s[46:47], v80, v158
	v_max3_f32 v15, v15, v194, v195
	s_nop 0
	v_cndmask_b32_e32 v196, v242, v196, vcc
	v_cndmask_b32_e64 v197, v242, v197, s[46:47]
	v_max3_f32 v15, v15, v196, v197
	s_and_saveexec_b64 s[2:3], s[38:39]
	ds_write_b32 v81, v194
	ds_write_b32 v81, v195 offset:32
	ds_write_b32 v81, v196 offset:64
	ds_write_b32 v81, v197 offset:96
	s_or_b64 exec, exec, s[2:3]
	s_waitcnt vmcnt(7)
	ds_write_b128 v198, v[90:93]
	ds_write_b128 v198, v[94:97] offset:1152
	ds_read_b128 v[90:93], v199
	ds_read_b128 v[94:97], v199 offset:64
	s_waitcnt lgkmcnt(8)
;   __device__ __forceinline__ half_t* mm() const { return (half_t*)(ws() + OFF_mm); }
; __device__ __forceinline__ void dsa_item(const KP& p, int b, int tile, char* smem) {
;     ...
; #pragma unroll 1
;     for (int mg = 0; mg < 2; ++mg) {
; #pragma unroll
;       for (int mm = 0; mm < 8; ++mm) {
;         const int m = mg * 8 + mm;
;         const int pos = m * 16 + col;
;         const int s = (pos < nsel) ? (int)sel[tk * 256 + pos] : 0;
;         const half_t* kp = ub + (size_t)s * NU + C_BK + hq * 8;
;         const h8 a0 = *(const h8*)kp, a1 = *(const h8*)(kp + 32);
;         f32x4 d = {0.f, 0.f, 0.f, 0.f};
;         d = __builtin_amdgcn_mfma_f32_16x16x32_f16(a0, q0, d, 0, 0, 0);
;         d = __builtin_amdgcn_mfma_f32_16x16x32_f16(a1, q1, d, 0, 0, 0);
; #pragma unroll
;         for (int r = 0; r < 4; ++r) {
;           const int pp = m * 16 + hq * 4 + r;
;           const float v = (pp < nsel) ? d[r] * 0.125f : NEGF;
;           mx = fmaxf(mx, v);
;           if (col < 8) pbuf[pp * 8 + col] = v;
;         }
;       }
;     }
	v_mfma_f32_16x16x32_f16 v[194:197], v[72:75], v[6:9], 0
	v_mfma_f32_16x16x32_f16 v[194:197], v[76:79], v[2:5], v[194:197]
	v_or_b32_e32 v80, 0x60, v160
	v_mul_f32_e32 v10, 0x3e000000, v10
	v_mul_f32_e32 v11, 0x3e000000, v11
	v_mul_f32_e32 v12, 0x3e000000, v12
	v_mul_f32_e32 v13, 0x3e000000, v13
	v_cmp_lt_i32_e32 vcc, v80, v85
	v_cmp_lt_i32_e64 s[46:47], v80, v171
	v_lshl_add_u32 v81, v80, 5, v167
	s_nop 0
	v_cndmask_b32_e32 v10, v242, v10, vcc
	v_cndmask_b32_e64 v11, v242, v11, s[46:47]
	v_cmp_lt_i32_e32 vcc, v80, v156
	v_cmp_lt_i32_e64 s[46:47], v80, v158
	v_max3_f32 v15, v15, v10, v11
	s_nop 0
	v_cndmask_b32_e32 v12, v242, v12, vcc
	v_cndmask_b32_e64 v13, v242, v13, s[46:47]
	v_max3_f32 v15, v15, v12, v13
	s_and_saveexec_b64 s[2:3], s[38:39]
	ds_write_b32 v81, v10
	ds_write_b32 v81, v11 offset:32
	ds_write_b32 v81, v12 offset:64
	ds_write_b32 v81, v13 offset:96
	s_or_b64 exec, exec, s[2:3]
	s_waitcnt vmcnt(6)
	ds_write_b128 v198, v[98:101]
	ds_write_b128 v198, v[102:105] offset:1152
	ds_read_b128 v[98:101], v199
	ds_read_b128 v[102:105], v199 offset:64
	s_waitcnt lgkmcnt(8)
	v_mfma_f32_16x16x32_f16 v[10:13], v[90:93], v[6:9], 0
	v_mfma_f32_16x16x32_f16 v[10:13], v[94:97], v[2:5], v[10:13]
	v_or_b32_e32 v80, 0x70, v160
	v_mul_f32_e32 v194, 0x3e000000, v194
	v_mul_f32_e32 v195, 0x3e000000, v195
	v_mul_f32_e32 v196, 0x3e000000, v196
	v_mul_f32_e32 v197, 0x3e000000, v197
	v_cmp_lt_i32_e32 vcc, v80, v85
	v_cmp_lt_i32_e64 s[46:47], v80, v171
	v_lshl_add_u32 v81, v80, 5, v167
	s_nop 0
	v_cndmask_b32_e32 v194, v242, v194, vcc
	v_cndmask_b32_e64 v195, v242, v195, s[46:47]
	v_cmp_lt_i32_e32 vcc, v80, v156
	v_cmp_lt_i32_e64 s[46:47], v80, v158
	v_max3_f32 v15, v15, v194, v195
	s_nop 0
	v_cndmask_b32_e32 v196, v242, v196, vcc
	v_cndmask_b32_e64 v197, v242, v197, s[46:47]
	v_max3_f32 v15, v15, v196, v197
	s_and_saveexec_b64 s[2:3], s[38:39]
	ds_write_b32 v81, v194
	ds_write_b32 v81, v195 offset:32
	ds_write_b32 v81, v196 offset:64
	ds_write_b32 v81, v197 offset:96
	s_or_b64 exec, exec, s[2:3]
	s_waitcnt vmcnt(5)
	ds_write_b128 v198, v[106:109]
	ds_write_b128 v198, v[110:113] offset:1152
	ds_read_b128 v[106:109], v199
	ds_read_b128 v[110:113], v199 offset:64
	s_waitcnt lgkmcnt(8)
	v_mfma_f32_16x16x32_f16 v[194:197], v[98:101], v[6:9], 0
	v_mfma_f32_16x16x32_f16 v[194:197], v[102:105], v[2:5], v[194:197]
	v_or_b32_e32 v80, 0x80, v160
	v_mul_f32_e32 v10, 0x3e000000, v10
	v_mul_f32_e32 v11, 0x3e000000, v11
	v_mul_f32_e32 v12, 0x3e000000, v12
	v_mul_f32_e32 v13, 0x3e000000, v13
	v_cmp_lt_i32_e32 vcc, v80, v85
	v_cmp_lt_i32_e64 s[46:47], v80, v171
	v_lshl_add_u32 v81, v80, 5, v167
	s_nop 0
	v_cndmask_b32_e32 v10, v242, v10, vcc
	v_cndmask_b32_e64 v11, v242, v11, s[46:47]
	v_cmp_lt_i32_e32 vcc, v80, v156
	v_cmp_lt_i32_e64 s[46:47], v80, v158
	v_max3_f32 v15, v15, v10, v11
	s_nop 0
	v_cndmask_b32_e32 v12, v242, v12, vcc
	v_cndmask_b32_e64 v13, v242, v13, s[46:47]
	v_max3_f32 v15, v15, v12, v13
	s_and_saveexec_b64 s[2:3], s[38:39]
	ds_write_b32 v81, v10
	ds_write_b32 v81, v11 offset:32
	ds_write_b32 v81, v12 offset:64
	ds_write_b32 v81, v13 offset:96
	s_or_b64 exec, exec, s[2:3]
	s_waitcnt vmcnt(4)
	ds_write_b128 v198, v[114:117]
	ds_write_b128 v198, v[118:121] offset:1152
	ds_read_b128 v[114:117], v199
	ds_read_b128 v[118:121], v199 offset:64
	s_waitcnt lgkmcnt(8)
	v_mfma_f32_16x16x32_f16 v[10:13], v[106:109], v[6:9], 0
	v_mfma_f32_16x16x32_f16 v[10:13], v[110:113], v[2:5], v[10:13]
	v_or_b32_e32 v80, 0x90, v160
	v_mul_f32_e32 v194, 0x3e000000, v194
	v_mul_f32_e32 v195, 0x3e000000, v195
	v_mul_f32_e32 v196, 0x3e000000, v196
	v_mul_f32_e32 v197, 0x3e000000, v197
	v_cmp_lt_i32_e32 vcc, v80, v85
	v_cmp_lt_i32_e64 s[46:47], v80, v171
	v_lshl_add_u32 v81, v80, 5, v167
	s_nop 0
	v_cndmask_b32_e32 v194, v242, v194, vcc
	v_cndmask_b32_e64 v195, v242, v195, s[46:47]
	v_cmp_lt_i32_e32 vcc, v80, v156
	v_cmp_lt_i32_e64 s[46:47], v80, v158
	v_max3_f32 v15, v15, v194, v195
	s_nop 0
	v_cndmask_b32_e32 v196, v242, v196, vcc
	v_cndmask_b32_e64 v197, v242, v197, s[46:47]
	v_max3_f32 v15, v15, v196, v197
	s_and_saveexec_b64 s[2:3], s[38:39]
	ds_write_b32 v81, v194
	ds_write_b32 v81, v195 offset:32
	ds_write_b32 v81, v196 offset:64
	ds_write_b32 v81, v197 offset:96
	s_or_b64 exec, exec, s[2:3]
	s_waitcnt vmcnt(3)
	ds_write_b128 v198, v[122:125]
	ds_write_b128 v198, v[128:131] offset:1152
	ds_read_b128 v[122:125], v199
	ds_read_b128 v[128:131], v199 offset:64
	s_waitcnt lgkmcnt(8)
	v_mfma_f32_16x16x32_f16 v[194:197], v[114:117], v[6:9], 0
	v_mfma_f32_16x16x32_f16 v[194:197], v[118:121], v[2:5], v[194:197]
	v_or_b32_e32 v80, 0xa0, v160
	v_mul_f32_e32 v10, 0x3e000000, v10
	v_mul_f32_e32 v11, 0x3e000000, v11
	v_mul_f32_e32 v12, 0x3e000000, v12
	v_mul_f32_e32 v13, 0x3e000000, v13
	v_cmp_lt_i32_e32 vcc, v80, v85
	v_cmp_lt_i32_e64 s[46:47], v80, v171
	v_lshl_add_u32 v81, v80, 5, v167
	s_nop 0
	v_cndmask_b32_e32 v10, v242, v10, vcc
	v_cndmask_b32_e64 v11, v242, v11, s[46:47]
	v_cmp_lt_i32_e32 vcc, v80, v156
	v_cmp_lt_i32_e64 s[46:47], v80, v158
	v_max3_f32 v15, v15, v10, v11
	s_nop 0
	v_cndmask_b32_e32 v12, v242, v12, vcc
	v_cndmask_b32_e64 v13, v242, v13, s[46:47]
	v_max3_f32 v15, v15, v12, v13
	s_and_saveexec_b64 s[2:3], s[38:39]
	ds_write_b32 v81, v10
	ds_write_b32 v81, v11 offset:32
	ds_write_b32 v81, v12 offset:64
	ds_write_b32 v81, v13 offset:96
	s_or_b64 exec, exec, s[2:3]
	s_waitcnt vmcnt(2)
;   __device__ __forceinline__ half_t* mm() const { return (half_t*)(ws() + OFF_mm); }
; __device__ __forceinline__ void dsa_item(const KP& p, int b, int tile, char* smem) {
;     ...
; #pragma unroll 1
;     for (int mg = 0; mg < 2; ++mg) {
; #pragma unroll
;       for (int mm = 0; mm < 8; ++mm) {
;         const int m = mg * 8 + mm;
;         const int pos = m * 16 + col;
;         const int s = (pos < nsel) ? (int)sel[tk * 256 + pos] : 0;
;         const half_t* kp = ub + (size_t)s * NU + C_BK + hq * 8;
;         const h8 a0 = *(const h8*)kp, a1 = *(const h8*)(kp + 32);
;         f32x4 d = {0.f, 0.f, 0.f, 0.f};
;         d = __builtin_amdgcn_mfma_f32_16x16x32_f16(a0, q0, d, 0, 0, 0);
;         d = __builtin_amdgcn_mfma_f32_16x16x32_f16(a1, q1, d, 0, 0, 0);
; #pragma unroll
;         for (int r = 0; r < 4; ++r) {
;           const int pp = m * 16 + hq * 4 + r;
;           const float v = (pp < nsel) ? d[r] * 0.125f : NEGF;
;           mx = fmaxf(mx, v);
;           if (col < 8) pbuf[pp * 8 + col] = v;
;         }
;       }
;     }
	ds_write_b128 v198, v[132:135]
	ds_write_b128 v198, v[136:139] offset:1152
	ds_read_b128 v[132:135], v199
	ds_read_b128 v[136:139], v199 offset:64
	s_waitcnt lgkmcnt(8)
	v_mfma_f32_16x16x32_f16 v[10:13], v[122:125], v[6:9], 0
	v_mfma_f32_16x16x32_f16 v[10:13], v[128:131], v[2:5], v[10:13]
	v_or_b32_e32 v80, 0xb0, v160
	v_mul_f32_e32 v194, 0x3e000000, v194
	v_mul_f32_e32 v195, 0x3e000000, v195
	v_mul_f32_e32 v196, 0x3e000000, v196
	v_mul_f32_e32 v197, 0x3e000000, v197
	v_cmp_lt_i32_e32 vcc, v80, v85
	v_cmp_lt_i32_e64 s[46:47], v80, v171
	v_lshl_add_u32 v81, v80, 5, v167
	s_nop 0
	v_cndmask_b32_e32 v194, v242, v194, vcc
	v_cndmask_b32_e64 v195, v242, v195, s[46:47]
	v_cmp_lt_i32_e32 vcc, v80, v156
	v_cmp_lt_i32_e64 s[46:47], v80, v158
	v_max3_f32 v15, v15, v194, v195
	s_nop 0
	v_cndmask_b32_e32 v196, v242, v196, vcc
	v_cndmask_b32_e64 v197, v242, v197, s[46:47]
	v_max3_f32 v15, v15, v196, v197
	s_and_saveexec_b64 s[2:3], s[38:39]
	ds_write_b32 v81, v194
	ds_write_b32 v81, v195 offset:32
	ds_write_b32 v81, v196 offset:64
	ds_write_b32 v81, v197 offset:96
	s_or_b64 exec, exec, s[2:3]
	s_waitcnt vmcnt(1)
	ds_write_b128 v198, v[140:143]
	ds_write_b128 v198, v[144:147] offset:1152
	ds_read_b128 v[140:143], v199
	ds_read_b128 v[144:147], v199 offset:64
	s_waitcnt lgkmcnt(8)
	v_mfma_f32_16x16x32_f16 v[194:197], v[132:135], v[6:9], 0
	v_mfma_f32_16x16x32_f16 v[194:197], v[136:139], v[2:5], v[194:197]
	v_or_b32_e32 v80, 0xc0, v160
	v_mul_f32_e32 v10, 0x3e000000, v10
	v_mul_f32_e32 v11, 0x3e000000, v11
	v_mul_f32_e32 v12, 0x3e000000, v12
	v_mul_f32_e32 v13, 0x3e000000, v13
	v_cmp_lt_i32_e32 vcc, v80, v85
	v_cmp_lt_i32_e64 s[46:47], v80, v171
	v_lshl_add_u32 v81, v80, 5, v167
	s_nop 0
	v_cndmask_b32_e32 v10, v242, v10, vcc
	v_cndmask_b32_e64 v11, v242, v11, s[46:47]
	v_cmp_lt_i32_e32 vcc, v80, v156
	v_cmp_lt_i32_e64 s[46:47], v80, v158
	v_max3_f32 v15, v15, v10, v11
	s_nop 0
	v_cndmask_b32_e32 v12, v242, v12, vcc
	v_cndmask_b32_e64 v13, v242, v13, s[46:47]
	v_max3_f32 v15, v15, v12, v13
	s_and_saveexec_b64 s[2:3], s[38:39]
	ds_write_b32 v81, v10
	ds_write_b32 v81, v11 offset:32
	ds_write_b32 v81, v12 offset:64
	ds_write_b32 v81, v13 offset:96
	s_or_b64 exec, exec, s[2:3]
	s_waitcnt vmcnt(0)
	ds_write_b128 v198, v[148:151]
	ds_write_b128 v198, v[152:155] offset:1152
	ds_read_b128 v[148:151], v199
	ds_read_b128 v[152:155], v199 offset:64
	s_waitcnt lgkmcnt(8)
	v_mfma_f32_16x16x32_f16 v[10:13], v[140:143], v[6:9], 0
	v_mfma_f32_16x16x32_f16 v[10:13], v[144:147], v[2:5], v[10:13]
	v_or_b32_e32 v80, 0xd0, v160
	v_mul_f32_e32 v194, 0x3e000000, v194
	v_mul_f32_e32 v195, 0x3e000000, v195
	v_mul_f32_e32 v196, 0x3e000000, v196
	v_mul_f32_e32 v197, 0x3e000000, v197
	v_cmp_lt_i32_e32 vcc, v80, v85
	v_cmp_lt_i32_e64 s[46:47], v80, v171
	v_lshl_add_u32 v81, v80, 5, v167
	s_nop 0
	v_cndmask_b32_e32 v194, v242, v194, vcc
	v_cndmask_b32_e64 v195, v242, v195, s[46:47]
	v_cmp_lt_i32_e32 vcc, v80, v156
	v_cmp_lt_i32_e64 s[46:47], v80, v158
	v_max3_f32 v15, v15, v194, v195
	s_nop 0
	v_cndmask_b32_e32 v196, v242, v196, vcc
	v_cndmask_b32_e64 v197, v242, v197, s[46:47]
	v_max3_f32 v15, v15, v196, v197
	s_and_saveexec_b64 s[2:3], s[38:39]
	ds_write_b32 v81, v194
	ds_write_b32 v81, v195 offset:32
	ds_write_b32 v81, v196 offset:64
	ds_write_b32 v81, v197 offset:96
	s_or_b64 exec, exec, s[2:3]
	s_waitcnt lgkmcnt(4)
	v_mfma_f32_16x16x32_f16 v[194:197], v[148:151], v[6:9], 0
	v_mfma_f32_16x16x32_f16 v[194:197], v[152:155], v[2:5], v[194:197]
	v_or_b32_e32 v80, 0xe0, v160
	v_mul_f32_e32 v10, 0x3e000000, v10
	v_mul_f32_e32 v11, 0x3e000000, v11
	v_mul_f32_e32 v12, 0x3e000000, v12
	v_mul_f32_e32 v13, 0x3e000000, v13
	v_cmp_lt_i32_e32 vcc, v80, v85
	v_cmp_lt_i32_e64 s[46:47], v80, v171
	v_lshl_add_u32 v81, v80, 5, v167
	s_nop 0
	v_cndmask_b32_e32 v10, v242, v10, vcc
	v_cndmask_b32_e64 v11, v242, v11, s[46:47]
	v_cmp_lt_i32_e32 vcc, v80, v156
	v_cmp_lt_i32_e64 s[46:47], v80, v158
	v_max3_f32 v15, v15, v10, v11
	s_nop 0
	v_cndmask_b32_e32 v12, v242, v12, vcc
	v_cndmask_b32_e64 v13, v242, v13, s[46:47]
	v_max3_f32 v15, v15, v12, v13
	s_and_saveexec_b64 s[2:3], s[38:39]
	ds_write_b32 v81, v10
	ds_write_b32 v81, v11 offset:32
	ds_write_b32 v81, v12 offset:64
	ds_write_b32 v81, v13 offset:96
	s_or_b64 exec, exec, s[2:3]
	s_nop 7
	v_or_b32_e32 v80, 0xf0, v160
	v_mul_f32_e32 v194, 0x3e000000, v194
	v_mul_f32_e32 v195, 0x3e000000, v195
	v_mul_f32_e32 v196, 0x3e000000, v196
	v_mul_f32_e32 v197, 0x3e000000, v197
	v_cmp_lt_i32_e32 vcc, v80, v85
	v_cmp_lt_i32_e64 s[46:47], v80, v171
	v_lshl_add_u32 v81, v80, 5, v167
	s_nop 0
	v_cndmask_b32_e32 v194, v242, v194, vcc
	v_cndmask_b32_e64 v195, v242, v195, s[46:47]
	v_cmp_lt_i32_e32 vcc, v80, v156
	v_cmp_lt_i32_e64 s[46:47], v80, v158
	v_max3_f32 v15, v15, v194, v195
	s_nop 0
	v_cndmask_b32_e32 v196, v242, v196, vcc
	v_cndmask_b32_e64 v197, v242, v197, s[46:47]
	v_max3_f32 v15, v15, v196, v197
	s_and_saveexec_b64 s[2:3], s[38:39]
	ds_write_b32 v81, v194
	ds_write_b32 v81, v195 offset:32
	ds_write_b32 v81, v196 offset:64
	ds_write_b32 v81, v197 offset:96
	s_or_b64 exec, exec, s[2:3]
